# grid barrier: XCD leader issues its cache invalidate right after its L2 writeback (before the cross-XCD wait) instead of after the release
# speedup vs baseline: 1.0081x; 1.0024x over previous
; __device__ __forceinline__ unsigned xb_ld(unsigned* p)              { return __hip_atomic_load(p, __ATOMIC_RELAXED, __HIP_MEMORY_SCOPE_AGENT); }
; __device__ __forceinline__ unsigned xb_add(unsigned* p, unsigned v) { return __hip_atomic_fetch_add(p, v, __ATOMIC_RELAXED, __HIP_MEMORY_SCOPE_AGENT); }
; #define XB_SPIN(cond, bar) do { unsigned _sp = 0; while (cond) { __builtin_amdgcn_s_sleep(1); \
;     if ((++_sp & 255u) == 0u) { if (xb_ld(&(bar)[XB_TMO])) break; if (_sp > XB_SPIN_CAP) { atomicAdd(&(bar)[XB_TMO], 1u); break; } } } } while (0)
; __device__ __forceinline__ void xcd_barrier(const XcdBarrier& b) {
;     ...
;         const unsigned old = xb_add(&bar[XB_XSUB(b.x)], 1u);
;         const unsigned gen = old / nloc;
;         if (old + 1u == (gen + 1u) * nloc) {
;             __builtin_amdgcn_fence(__ATOMIC_RELEASE, "agent");
;             asm volatile("s_waitcnt vmcnt(0)" ::: "memory");
;             const unsigned og = xb_add(&bar[XB_TOP], 1u);
;             const unsigned tg = og / nx;
;             if (og + 1u == (tg + 1u) * nx) xb_add(&bar[XB_TOPGEN], 1u);
;             else XB_SPIN(xb_ld(&bar[XB_TOPGEN]) == tg, bar);
;             __builtin_amdgcn_fence(__ATOMIC_ACQUIRE, "agent");
;             xb_add(&bar[XB_XGEN(b.x)], 1u);
;             asm volatile("s_waitcnt vmcnt(0)" ::: "memory");
.LBB0_77:
	s_andn2_saveexec_b64 s[0:1], s[18:19]
	s_cbranch_execz .LBB0_97
	s_mov_b64 s[0:1], exec
	buffer_wbl2 sc1
	s_waitcnt lgkmcnt(0)
	s_waitcnt vmcnt(0)
	buffer_inv sc1
	v_mbcnt_lo_u32_b32 v2, s0, 0
	v_mbcnt_hi_u32_b32 v2, s1, v2
	v_cmp_eq_u32_e32 vcc, 0, v2
	s_and_saveexec_b64 s[12:13], vcc
	s_cbranch_execz .LBB0_80
	s_bcnt1_i32_b64 s0, s[0:1]
	v_mov_b32_e32 v3, 0x7000
	v_mov_b32_e32 v4, s0
	global_atomic_add v3, v3, v4, s[78:79] offset:1024 sc0

; __device__ __forceinline__ unsigned xb_add(unsigned* p, unsigned v) { return __hip_atomic_fetch_add(p, v, __ATOMIC_RELAXED, __HIP_MEMORY_SCOPE_AGENT); }
; __device__ __forceinline__ void xcd_barrier(const XcdBarrier& b) {
;     ...
;             __builtin_amdgcn_fence(__ATOMIC_ACQUIRE, "agent");
;             xb_add(&bar[XB_XGEN(b.x)], 1u);
.LBB0_94:
	s_or_b64 exec, exec, s[0:1]
	s_mov_b64 s[0:1], exec
	v_mbcnt_lo_u32_b32 v1, s0, 0
	v_mbcnt_hi_u32_b32 v1, s1, v1
	v_cmp_eq_u32_e32 vcc, 0, v1
	s_waitcnt vmcnt(0)
	s_and_saveexec_b64 s[12:13], vcc
	s_cbranch_execz .LBB0_96
	s_bcnt1_i32_b64 s0, s[0:1]
	v_mov_b32_e32 v1, 0x2000
	v_mov_b32_e32 v2, s0
	global_atomic_add v1, v2, s[14:15] offset:1024

; __device__ __forceinline__ unsigned xb_add(unsigned* p, unsigned v) { return __hip_atomic_fetch_add(p, v, __ATOMIC_RELAXED, __HIP_MEMORY_SCOPE_AGENT); }
; __device__ __forceinline__ void xcd_barrier(const XcdBarrier& b) {
;     ...
;             __builtin_amdgcn_fence(__ATOMIC_ACQUIRE, "agent");
;             xb_add(&bar[XB_XGEN(b.x)], 1u);
.LBB0_248:
	s_or_b64 exec, exec, s[0:1]
	s_mov_b64 s[0:1], exec
	v_mbcnt_lo_u32_b32 v1, s0, 0
	v_mbcnt_hi_u32_b32 v1, s1, v1
	v_cmp_eq_u32_e32 vcc, 0, v1
	s_waitcnt vmcnt(0)
	s_and_saveexec_b64 s[12:13], vcc
	s_cbranch_execz .LBB0_250
	s_bcnt1_i32_b64 s0, s[0:1]
	v_mov_b32_e32 v1, 0x2000
	v_mov_b32_e32 v2, s0
	global_atomic_add v1, v2, s[6:7] offset:1024

; __device__ __forceinline__ unsigned xb_add(unsigned* p, unsigned v) { return __hip_atomic_fetch_add(p, v, __ATOMIC_RELAXED, __HIP_MEMORY_SCOPE_AGENT); }
; __device__ __forceinline__ void xcd_barrier(const XcdBarrier& b) {
;     ...
;         const unsigned old = xb_add(&bar[XB_XSUB(b.x)], 1u);
;         const unsigned gen = old / nloc;
;         if (old + 1u == (gen + 1u) * nloc) {
;             __builtin_amdgcn_fence(__ATOMIC_RELEASE, "agent");
;             asm volatile("s_waitcnt vmcnt(0)" ::: "memory");
;             const unsigned og = xb_add(&bar[XB_TOP], 1u);
.LBB0_345:
	s_andn2_saveexec_b64 s[0:1], s[20:21]
	s_cbranch_execz .LBB0_365
	s_mov_b64 s[0:1], exec
	buffer_wbl2 sc1
	s_waitcnt lgkmcnt(0)
	s_waitcnt vmcnt(0)
	buffer_inv sc1
	v_mbcnt_lo_u32_b32 v2, s0, 0
	v_mbcnt_hi_u32_b32 v2, s1, v2
	v_cmp_eq_u32_e32 vcc, 0, v2
	s_and_saveexec_b64 s[12:13], vcc
	s_cbranch_execz .LBB0_348
	s_bcnt1_i32_b64 s0, s[0:1]
	v_mov_b32_e32 v3, 0x7000
	v_mov_b32_e32 v4, s0
	global_atomic_add v3, v3, v4, s[78:79] offset:1024 sc0

; __device__ __forceinline__ unsigned xb_add(unsigned* p, unsigned v) { return __hip_atomic_fetch_add(p, v, __ATOMIC_RELAXED, __HIP_MEMORY_SCOPE_AGENT); }
; __device__ __forceinline__ void xcd_barrier(const XcdBarrier& b) {
;     ...
;         const unsigned old = xb_add(&bar[XB_XSUB(b.x)], 1u);
;         const unsigned gen = old / nloc;
;         if (old + 1u == (gen + 1u) * nloc) {
;             __builtin_amdgcn_fence(__ATOMIC_RELEASE, "agent");
;             asm volatile("s_waitcnt vmcnt(0)" ::: "memory");
;             const unsigned og = xb_add(&bar[XB_TOP], 1u);
.LBB0_538:
	s_andn2_saveexec_b64 s[0:1], s[8:9]
	s_cbranch_execz .LBB0_558
	s_mov_b64 s[0:1], exec
	buffer_wbl2 sc1
	s_waitcnt lgkmcnt(0)
	s_waitcnt vmcnt(0)
	buffer_inv sc1
	v_mbcnt_lo_u32_b32 v2, s0, 0
	v_mbcnt_hi_u32_b32 v2, s1, v2
	v_cmp_eq_u32_e32 vcc, 0, v2
	s_and_saveexec_b64 s[8:9], vcc
	s_cbranch_execz .LBB0_541
	s_bcnt1_i32_b64 s0, s[0:1]
	v_mov_b32_e32 v3, 0x7000
	v_mov_b32_e32 v4, s0
	global_atomic_add v3, v3, v4, s[78:79] offset:1024 sc0

; __device__ __forceinline__ unsigned xb_add(unsigned* p, unsigned v) { return __hip_atomic_fetch_add(p, v, __ATOMIC_RELAXED, __HIP_MEMORY_SCOPE_AGENT); }
; __device__ __forceinline__ void xcd_barrier(const XcdBarrier& b) {
;     ...
;             __builtin_amdgcn_fence(__ATOMIC_ACQUIRE, "agent");
;             xb_add(&bar[XB_XGEN(b.x)], 1u);
.LBB0_555:
	s_or_b64 exec, exec, s[0:1]
	s_mov_b64 s[0:1], exec
	v_mbcnt_lo_u32_b32 v1, s0, 0
	v_mbcnt_hi_u32_b32 v1, s1, v1
	v_cmp_eq_u32_e32 vcc, 0, v1
	s_waitcnt vmcnt(0)
	s_and_saveexec_b64 s[8:9], vcc
	s_cbranch_execz .LBB0_557
	s_bcnt1_i32_b64 s0, s[0:1]
	v_mov_b32_e32 v1, 0x2000
	v_mov_b32_e32 v2, s0
	global_atomic_add v1, v2, s[6:7] offset:1024

; __device__ __forceinline__ unsigned xb_add(unsigned* p, unsigned v) { return __hip_atomic_fetch_add(p, v, __ATOMIC_RELAXED, __HIP_MEMORY_SCOPE_AGENT); }
; __device__ __forceinline__ void xcd_barrier(const XcdBarrier& b) {
;     ...
;         const unsigned old = xb_add(&bar[XB_XSUB(b.x)], 1u);
;         const unsigned gen = old / nloc;
;         if (old + 1u == (gen + 1u) * nloc) {
;             __builtin_amdgcn_fence(__ATOMIC_RELEASE, "agent");
;             asm volatile("s_waitcnt vmcnt(0)" ::: "memory");
;             const unsigned og = xb_add(&bar[XB_TOP], 1u);
.LBB0_1218:
	s_andn2_saveexec_b64 s[6:7], s[6:7]
	s_cbranch_execz .LBB0_1238
	s_mov_b64 s[6:7], exec
	buffer_wbl2 sc1
	s_waitcnt lgkmcnt(0)
	s_waitcnt vmcnt(0)
	buffer_inv sc1
	v_mbcnt_lo_u32_b32 v2, s6, 0
	v_mbcnt_hi_u32_b32 v2, s7, v2
	v_cmp_eq_u32_e32 vcc, 0, v2
	s_and_saveexec_b64 s[12:13], vcc
	s_cbranch_execz .LBB0_1221
	s_bcnt1_i32_b64 s3, s[6:7]
	v_mov_b32_e32 v3, 0x7000
	v_mov_b32_e32 v4, s3
	global_atomic_add v3, v3, v4, s[78:79] offset:1024 sc0

; __device__ __forceinline__ unsigned xb_add(unsigned* p, unsigned v) { return __hip_atomic_fetch_add(p, v, __ATOMIC_RELAXED, __HIP_MEMORY_SCOPE_AGENT); }
; __device__ __forceinline__ void xcd_barrier(const XcdBarrier& b) {
;     ...
;             __builtin_amdgcn_fence(__ATOMIC_ACQUIRE, "agent");
;             xb_add(&bar[XB_XGEN(b.x)], 1u);
.LBB0_1235:
	s_or_b64 exec, exec, s[6:7]
	s_mov_b64 s[6:7], exec
	v_mbcnt_lo_u32_b32 v1, s6, 0
	v_mbcnt_hi_u32_b32 v1, s7, v1
	v_cmp_eq_u32_e32 vcc, 0, v1
	s_waitcnt vmcnt(0)
	s_and_saveexec_b64 s[12:13], vcc
	s_cbranch_execz .LBB0_1237
	s_bcnt1_i32_b64 s3, s[6:7]
	v_mov_b32_e32 v1, 0x2000
	v_mov_b32_e32 v2, s3
	global_atomic_add v1, v2, s[0:1] offset:1024
